# attention: the -1e30 score initialisation (32 v_mov per step) moved into the masked-tile path only
# speedup vs baseline: 1.0183x; 1.0073x over previous
.LBB0_397:
	s_and_b32 s38, s74, 0x10000
	s_add_i32 s76, s38, 0
	s_cmp_lg_u32 s72, s74
	s_cselect_b64 s[38:39], -1, 0
	v_xor_b32_e32 v116, 0x80000000, v163
	s_or_b64 s[64:65], s[62:63], s[38:39]
	v_mov_b32_e32 v117, v116
	v_mov_b32_e32 v118, v116
	v_mov_b32_e32 v119, v116
	v_add_u32_e32 v2, s76, v154
	ds_read_b128 v[84:87], v2
	v_add_u32_e32 v0, s76, v155
	ds_read_b128 v[88:91], v0
	ds_read_b128 v[92:95], v2 offset:4096
	s_waitcnt lgkmcnt(2)
	v_mfma_f32_16x16x32_bf16 v[84:87], v[84:87], v[28:31], v[116:119]
	ds_read_b128 v[96:99], v0 offset:4096
	s_waitcnt lgkmcnt(2)
	v_mfma_f32_16x16x32_bf16 v[84:87], v[88:91], v[32:35], v[84:87]
	ds_read_b128 v[88:91], v2 offset:8192
	s_waitcnt lgkmcnt(2)
	v_mfma_f32_16x16x32_bf16 v[92:95], v[92:95], v[28:31], v[116:119]
	ds_read_b128 v[100:103], v0 offset:8192
	s_waitcnt lgkmcnt(2)
	v_mfma_f32_16x16x32_bf16 v[92:95], v[96:99], v[32:35], v[92:95]
	ds_read_b128 v[104:107], v2 offset:12288
	s_waitcnt lgkmcnt(2)
	v_mfma_f32_16x16x32_bf16 v[88:91], v[88:91], v[28:31], v[116:119]
	ds_read_b128 v[108:111], v0 offset:12288
	s_waitcnt lgkmcnt(2)
	v_mfma_f32_16x16x32_bf16 v[96:99], v[100:103], v[32:35], v[88:91]
	s_waitcnt lgkmcnt(1)
	v_mfma_f32_16x16x32_bf16 v[88:91], v[104:107], v[28:31], v[116:119]
	s_waitcnt lgkmcnt(0)
	v_mfma_f32_16x16x32_bf16 v[88:91], v[108:111], v[32:35], v[88:91]
	s_and_b64 vcc, exec, s[64:65]
	s_cbranch_vccnz .Latt_u1_1
	v_mov_b32_e32 v100, 0xf149f2ca
	v_mov_b32_e32 v101, 0xf149f2ca
	v_mov_b32_e32 v102, 0xf149f2ca
	v_mov_b32_e32 v103, 0xf149f2ca
	v_mov_b32_e32 v104, 0xf149f2ca
	v_mov_b32_e32 v105, 0xf149f2ca
	v_mov_b32_e32 v106, 0xf149f2ca
	v_mov_b32_e32 v107, 0xf149f2ca
	v_mov_b32_e32 v108, 0xf149f2ca
	v_mov_b32_e32 v109, 0xf149f2ca
	v_mov_b32_e32 v110, 0xf149f2ca
	v_mov_b32_e32 v111, 0xf149f2ca
	v_mov_b32_e32 v112, 0xf149f2ca
	v_mov_b32_e32 v113, 0xf149f2ca
	v_mov_b32_e32 v114, 0xf149f2ca
	v_mov_b32_e32 v115, 0xf149f2ca
	s_branch .LBB0_399
.Latt_u1_1:
	ds_read_b128 v[100:103], v2 offset:32768
	ds_read_b128 v[104:107], v0 offset:32768
	ds_read_b128 v[108:111], v2 offset:36864
	s_waitcnt lgkmcnt(2)
	v_mfma_f32_16x16x32_bf16 v[100:103], v[100:103], v[28:31], v[116:119]
	ds_read_b128 v[120:123], v0 offset:36864
	s_waitcnt lgkmcnt(2)
	v_mfma_f32_16x16x32_bf16 v[112:115], v[104:107], v[32:35], v[100:103]
	s_nop 4
	ds_read_b128 v[100:103], v2 offset:40960
	s_waitcnt lgkmcnt(2)
	v_mfma_f32_16x16x32_bf16 v[104:107], v[108:111], v[28:31], v[116:119]
	ds_read_b128 v[124:127], v0 offset:40960
	s_waitcnt lgkmcnt(2)
	v_mfma_f32_16x16x32_bf16 v[108:111], v[120:123], v[32:35], v[104:107]
	ds_read_b128 v[120:123], v2 offset:45056
	s_waitcnt lgkmcnt(2)
	v_mfma_f32_16x16x32_bf16 v[100:103], v[100:103], v[28:31], v[116:119]
	ds_read_b128 v[128:131], v0 offset:45056
	s_waitcnt lgkmcnt(2)
	v_mfma_f32_16x16x32_bf16 v[104:107], v[124:127], v[32:35], v[100:103]
	s_waitcnt lgkmcnt(1)
	v_mfma_f32_16x16x32_bf16 v[100:103], v[120:123], v[28:31], v[116:119]
	s_waitcnt lgkmcnt(0)
	v_mfma_f32_16x16x32_bf16 v[100:103], v[128:131], v[32:35], v[100:103]

.LBB0_404:
	v_exp_f32_e32 v0, v84
	v_exp_f32_e32 v2, v85
	v_exp_f32_e32 v3, v86
	v_exp_f32_e32 v164, v87
	v_exp_f32_e32 v165, v92
	v_exp_f32_e32 v166, v93
	v_exp_f32_e32 v167, v94
	v_exp_f32_e32 v168, v95
	v_exp_f32_e32 v169, v96
	v_exp_f32_e32 v170, v97
	v_exp_f32_e32 v171, v98
	v_exp_f32_e32 v172, v99
	v_exp_f32_e32 v173, v88
	v_exp_f32_e32 v174, v89
	v_exp_f32_e32 v175, v90
	v_exp_f32_e32 v176, v91
	v_exp_f32_e32 v177, v112
	v_exp_f32_e32 v178, v113
	v_exp_f32_e32 v179, v114
	v_exp_f32_e32 v180, v115
	v_exp_f32_e32 v181, v108
	v_exp_f32_e32 v182, v109
	v_exp_f32_e32 v183, v110
	v_exp_f32_e32 v184, v111
	v_exp_f32_e32 v185, v104
	v_exp_f32_e32 v186, v105
	v_exp_f32_e32 v187, v106
	v_exp_f32_e32 v188, v107
	v_exp_f32_e32 v189, v100
	v_exp_f32_e32 v190, v101
	v_exp_f32_e32 v191, v102
	v_exp_f32_e32 v192, v103
	v_xor_b32_e32 v132, 0x80000000, v161
	v_mov_b32_e32 v133, v132
	v_mov_b32_e32 v134, v132
	v_mov_b32_e32 v135, v132
	v_cvt_pk_bf16_f32 v92, v0, v2
	v_cvt_pk_bf16_f32 v93, v3, v164
	v_cvt_pk_bf16_f32 v94, v165, v166
	v_cvt_pk_bf16_f32 v95, v167, v168
	v_cvt_pk_bf16_f32 v96, v169, v170
	v_cvt_pk_bf16_f32 v97, v171, v172
	v_cvt_pk_bf16_f32 v98, v173, v174
	v_cvt_pk_bf16_f32 v99, v175, v176
	v_cvt_pk_bf16_f32 v84, v177, v178
	v_cvt_pk_bf16_f32 v85, v179, v180
	v_cvt_pk_bf16_f32 v86, v181, v182
	v_cvt_pk_bf16_f32 v87, v183, v184
	v_cvt_pk_bf16_f32 v88, v185, v186
	v_cvt_pk_bf16_f32 v89, v187, v188
	v_cvt_pk_bf16_f32 v90, v189, v190
	v_cvt_pk_bf16_f32 v91, v191, v192
	v_add_u32_e32 v194, s76, v156
	ds_read_b128 v[100:103], v194
	v_add_u32_e32 v193, s76, v157
	ds_read_b128 v[104:107], v193
	ds_read_b128 v[108:111], v194 offset:4096
	s_waitcnt lgkmcnt(2)
	v_mfma_f32_16x16x32_bf16 v[100:103], v[100:103], v[36:39], v[132:135]
	ds_read_b128 v[112:115], v193 offset:4096
	s_waitcnt lgkmcnt(2)
	v_mfma_f32_16x16x32_bf16 v[100:103], v[104:107], v[40:43], v[100:103]
	ds_read_b128 v[104:107], v194 offset:8192
	s_waitcnt lgkmcnt(2)
	v_mfma_f32_16x16x32_bf16 v[108:111], v[108:111], v[36:39], v[132:135]
	ds_read_b128 v[116:119], v193 offset:8192
	s_waitcnt lgkmcnt(2)
	v_mfma_f32_16x16x32_bf16 v[108:111], v[112:115], v[40:43], v[108:111]
	ds_read_b128 v[120:123], v194 offset:12288
	s_waitcnt lgkmcnt(2)
	v_mfma_f32_16x16x32_bf16 v[104:107], v[104:107], v[36:39], v[132:135]
	ds_read_b128 v[124:127], v193 offset:12288
	s_waitcnt lgkmcnt(2)
	v_mfma_f32_16x16x32_bf16 v[112:115], v[116:119], v[40:43], v[104:107]
	s_waitcnt lgkmcnt(1)
	v_mfma_f32_16x16x32_bf16 v[104:107], v[120:123], v[36:39], v[132:135]
	s_waitcnt lgkmcnt(0)
	v_mfma_f32_16x16x32_bf16 v[104:107], v[124:127], v[40:43], v[104:107]
	v_cndmask_b32_e64 v117, 0, 1, s[64:65]
	v_cmp_ne_u32_e64 s[38:39], 1, v117
	s_andn2_b64 vcc, exec, s[64:65]
	s_cbranch_vccz .Latt_u1_2
	v_mov_b32_e32 v116, 0xf149f2ca
	v_mov_b32_e32 v117, 0xf149f2ca
	v_mov_b32_e32 v118, 0xf149f2ca
	v_mov_b32_e32 v119, 0xf149f2ca
	v_mov_b32_e32 v120, 0xf149f2ca
	v_mov_b32_e32 v121, 0xf149f2ca
	v_mov_b32_e32 v122, 0xf149f2ca
	v_mov_b32_e32 v123, 0xf149f2ca
	v_mov_b32_e32 v124, 0xf149f2ca
	v_mov_b32_e32 v125, 0xf149f2ca
	v_mov_b32_e32 v126, 0xf149f2ca
	v_mov_b32_e32 v127, 0xf149f2ca
	v_mov_b32_e32 v128, 0xf149f2ca
	v_mov_b32_e32 v129, 0xf149f2ca
	v_mov_b32_e32 v130, 0xf149f2ca
	v_mov_b32_e32 v131, 0xf149f2ca
	s_branch .LBB0_406
.Latt_u1_2:
	ds_read_b128 v[116:119], v194 offset:32768
	ds_read_b128 v[120:123], v193 offset:32768
	ds_read_b128 v[124:127], v194 offset:36864
	s_waitcnt lgkmcnt(2)
	v_mfma_f32_16x16x32_bf16 v[116:119], v[116:119], v[36:39], v[132:135]
	ds_read_b128 v[206:209], v193 offset:36864
	s_waitcnt lgkmcnt(2)
	v_mfma_f32_16x16x32_bf16 v[128:131], v[120:123], v[40:43], v[116:119]
	s_nop 4
	ds_read_b128 v[116:119], v194 offset:40960
	s_waitcnt lgkmcnt(2)
	v_mfma_f32_16x16x32_bf16 v[120:123], v[124:127], v[36:39], v[132:135]
	ds_read_b128 v[210:213], v193 offset:40960
	s_waitcnt lgkmcnt(2)
	v_mfma_f32_16x16x32_bf16 v[124:127], v[206:209], v[40:43], v[120:123]
	ds_read_b128 v[206:209], v194 offset:45056
	s_waitcnt lgkmcnt(2)
	v_mfma_f32_16x16x32_bf16 v[116:119], v[116:119], v[36:39], v[132:135]
	ds_read_b128 v[214:217], v193 offset:45056
	s_waitcnt lgkmcnt(2)
	v_mfma_f32_16x16x32_bf16 v[120:123], v[210:213], v[40:43], v[116:119]
	s_waitcnt lgkmcnt(1)
	v_mfma_f32_16x16x32_bf16 v[116:119], v[206:209], v[36:39], v[132:135]
	s_waitcnt lgkmcnt(0)
	v_mfma_f32_16x16x32_bf16 v[116:119], v[214:217], v[40:43], v[116:119]

.LBB0_421:
	s_and_b32 s38, s55, 0x10000
	s_add_i32 s65, s38, 0
	s_cmp_lg_u32 s64, s55
	s_cselect_b64 s[38:39], -1, 0
	v_xor_b32_e32 v116, 0x80000000, v163
	s_or_b64 s[46:47], s[44:45], s[38:39]
	v_mov_b32_e32 v117, v116
	v_mov_b32_e32 v118, v116
	v_mov_b32_e32 v119, v116
	v_add_u32_e32 v2, s65, v154
	ds_read_b128 v[84:87], v2
	v_add_u32_e32 v0, s65, v155
	ds_read_b128 v[88:91], v0
	ds_read_b128 v[92:95], v2 offset:4096
	s_waitcnt lgkmcnt(2)
	v_mfma_f32_16x16x32_bf16 v[84:87], v[84:87], v[36:39], v[116:119]
	ds_read_b128 v[96:99], v0 offset:4096
	s_waitcnt lgkmcnt(2)
	v_mfma_f32_16x16x32_bf16 v[84:87], v[88:91], v[40:43], v[84:87]
	ds_read_b128 v[88:91], v2 offset:8192
	s_waitcnt lgkmcnt(2)
	v_mfma_f32_16x16x32_bf16 v[92:95], v[92:95], v[36:39], v[116:119]
	ds_read_b128 v[100:103], v0 offset:8192
	s_waitcnt lgkmcnt(2)
	v_mfma_f32_16x16x32_bf16 v[92:95], v[96:99], v[40:43], v[92:95]
	ds_read_b128 v[104:107], v2 offset:12288
	s_waitcnt lgkmcnt(2)
	v_mfma_f32_16x16x32_bf16 v[88:91], v[88:91], v[36:39], v[116:119]
	ds_read_b128 v[108:111], v0 offset:12288
	s_waitcnt lgkmcnt(2)
	v_mfma_f32_16x16x32_bf16 v[96:99], v[100:103], v[40:43], v[88:91]
	s_waitcnt lgkmcnt(1)
	v_mfma_f32_16x16x32_bf16 v[88:91], v[104:107], v[36:39], v[116:119]
	s_waitcnt lgkmcnt(0)
	v_mfma_f32_16x16x32_bf16 v[88:91], v[108:111], v[40:43], v[88:91]
	s_and_b64 vcc, exec, s[46:47]
	s_cbranch_vccnz .Latt_u1_3
	v_mov_b32_e32 v100, 0xf149f2ca
	v_mov_b32_e32 v101, 0xf149f2ca
	v_mov_b32_e32 v102, 0xf149f2ca
	v_mov_b32_e32 v103, 0xf149f2ca
	v_mov_b32_e32 v104, 0xf149f2ca
	v_mov_b32_e32 v105, 0xf149f2ca
	v_mov_b32_e32 v106, 0xf149f2ca
	v_mov_b32_e32 v107, 0xf149f2ca
	v_mov_b32_e32 v108, 0xf149f2ca
	v_mov_b32_e32 v109, 0xf149f2ca
	v_mov_b32_e32 v110, 0xf149f2ca
	v_mov_b32_e32 v111, 0xf149f2ca
	v_mov_b32_e32 v112, 0xf149f2ca
	v_mov_b32_e32 v113, 0xf149f2ca
	v_mov_b32_e32 v114, 0xf149f2ca
	v_mov_b32_e32 v115, 0xf149f2ca
	s_branch .LBB0_423
.Latt_u1_3:
	ds_read_b128 v[100:103], v2 offset:32768
	ds_read_b128 v[104:107], v0 offset:32768
	ds_read_b128 v[108:111], v2 offset:36864
	s_waitcnt lgkmcnt(2)
	v_mfma_f32_16x16x32_bf16 v[100:103], v[100:103], v[36:39], v[116:119]
	ds_read_b128 v[120:123], v0 offset:36864
	s_waitcnt lgkmcnt(2)
	v_mfma_f32_16x16x32_bf16 v[112:115], v[104:107], v[40:43], v[100:103]
	s_nop 4
	ds_read_b128 v[100:103], v2 offset:40960
	s_waitcnt lgkmcnt(2)
	v_mfma_f32_16x16x32_bf16 v[104:107], v[108:111], v[36:39], v[116:119]
	ds_read_b128 v[124:127], v0 offset:40960
	s_waitcnt lgkmcnt(2)
	v_mfma_f32_16x16x32_bf16 v[108:111], v[120:123], v[40:43], v[104:107]
	ds_read_b128 v[120:123], v2 offset:45056
	s_waitcnt lgkmcnt(2)
	v_mfma_f32_16x16x32_bf16 v[100:103], v[100:103], v[36:39], v[116:119]
	ds_read_b128 v[128:131], v0 offset:45056
	s_waitcnt lgkmcnt(2)
	v_mfma_f32_16x16x32_bf16 v[104:107], v[124:127], v[40:43], v[100:103]
	s_waitcnt lgkmcnt(1)
	v_mfma_f32_16x16x32_bf16 v[100:103], v[120:123], v[36:39], v[116:119]
	s_waitcnt lgkmcnt(0)
	v_mfma_f32_16x16x32_bf16 v[100:103], v[128:131], v[40:43], v[100:103]

.LBB0_428:
	v_exp_f32_e32 v0, v84
	v_exp_f32_e32 v2, v85
	v_exp_f32_e32 v3, v86
	v_exp_f32_e32 v164, v87
	v_exp_f32_e32 v165, v92
	v_exp_f32_e32 v166, v93
	v_exp_f32_e32 v167, v94
	v_exp_f32_e32 v168, v95
	v_exp_f32_e32 v169, v96
	v_exp_f32_e32 v170, v97
	v_exp_f32_e32 v171, v98
	v_exp_f32_e32 v172, v99
	v_exp_f32_e32 v173, v88
	v_exp_f32_e32 v174, v89
	v_exp_f32_e32 v175, v90
	v_exp_f32_e32 v176, v91
	v_exp_f32_e32 v177, v112
	v_exp_f32_e32 v178, v113
	v_exp_f32_e32 v179, v114
	v_exp_f32_e32 v180, v115
	v_exp_f32_e32 v181, v108
	v_exp_f32_e32 v182, v109
	v_exp_f32_e32 v183, v110
	v_exp_f32_e32 v184, v111
	v_exp_f32_e32 v185, v104
	v_exp_f32_e32 v186, v105
	v_exp_f32_e32 v187, v106
	v_exp_f32_e32 v188, v107
	v_exp_f32_e32 v189, v100
	v_exp_f32_e32 v190, v101
	v_exp_f32_e32 v191, v102
	v_exp_f32_e32 v192, v103
	v_xor_b32_e32 v132, 0x80000000, v161
	v_mov_b32_e32 v133, v132
	v_mov_b32_e32 v134, v132
	v_mov_b32_e32 v135, v132
	v_cvt_pk_bf16_f32 v92, v0, v2
	v_cvt_pk_bf16_f32 v93, v3, v164
	v_cvt_pk_bf16_f32 v94, v165, v166
	v_cvt_pk_bf16_f32 v95, v167, v168
	v_cvt_pk_bf16_f32 v96, v169, v170
	v_cvt_pk_bf16_f32 v97, v171, v172
	v_cvt_pk_bf16_f32 v98, v173, v174
	v_cvt_pk_bf16_f32 v99, v175, v176
	v_cvt_pk_bf16_f32 v84, v177, v178
	v_cvt_pk_bf16_f32 v85, v179, v180
	v_cvt_pk_bf16_f32 v86, v181, v182
	v_cvt_pk_bf16_f32 v87, v183, v184
	v_cvt_pk_bf16_f32 v88, v185, v186
	v_cvt_pk_bf16_f32 v89, v187, v188
	v_cvt_pk_bf16_f32 v90, v189, v190
	v_cvt_pk_bf16_f32 v91, v191, v192
	v_add_u32_e32 v194, s65, v156
	ds_read_b128 v[100:103], v194
	v_add_u32_e32 v193, s65, v157
	ds_read_b128 v[104:107], v193
	ds_read_b128 v[108:111], v194 offset:4096
	s_waitcnt lgkmcnt(2)
	v_mfma_f32_16x16x32_bf16 v[100:103], v[100:103], v[44:47], v[132:135]
	ds_read_b128 v[112:115], v193 offset:4096
	s_waitcnt lgkmcnt(2)
	v_mfma_f32_16x16x32_bf16 v[100:103], v[104:107], v[52:55], v[100:103]
	ds_read_b128 v[104:107], v194 offset:8192
	s_waitcnt lgkmcnt(2)
	v_mfma_f32_16x16x32_bf16 v[108:111], v[108:111], v[44:47], v[132:135]
	ds_read_b128 v[116:119], v193 offset:8192
	s_waitcnt lgkmcnt(2)
	v_mfma_f32_16x16x32_bf16 v[108:111], v[112:115], v[52:55], v[108:111]
	ds_read_b128 v[120:123], v194 offset:12288
	s_waitcnt lgkmcnt(2)
	v_mfma_f32_16x16x32_bf16 v[104:107], v[104:107], v[44:47], v[132:135]
	ds_read_b128 v[124:127], v193 offset:12288
	s_waitcnt lgkmcnt(2)
	v_mfma_f32_16x16x32_bf16 v[112:115], v[116:119], v[52:55], v[104:107]
	s_waitcnt lgkmcnt(1)
	v_mfma_f32_16x16x32_bf16 v[104:107], v[120:123], v[44:47], v[132:135]
	s_waitcnt lgkmcnt(0)
	v_mfma_f32_16x16x32_bf16 v[104:107], v[124:127], v[52:55], v[104:107]
	v_cndmask_b32_e64 v117, 0, 1, s[46:47]
	v_cmp_ne_u32_e64 s[38:39], 1, v117
	s_andn2_b64 vcc, exec, s[46:47]
	s_cbranch_vccz .Latt_u1_4
	v_mov_b32_e32 v116, 0xf149f2ca
	v_mov_b32_e32 v117, 0xf149f2ca
	v_mov_b32_e32 v118, 0xf149f2ca
	v_mov_b32_e32 v119, 0xf149f2ca
	v_mov_b32_e32 v120, 0xf149f2ca
	v_mov_b32_e32 v121, 0xf149f2ca
	v_mov_b32_e32 v122, 0xf149f2ca
	v_mov_b32_e32 v123, 0xf149f2ca
	v_mov_b32_e32 v124, 0xf149f2ca
	v_mov_b32_e32 v125, 0xf149f2ca
	v_mov_b32_e32 v126, 0xf149f2ca
	v_mov_b32_e32 v127, 0xf149f2ca
	v_mov_b32_e32 v128, 0xf149f2ca
	v_mov_b32_e32 v129, 0xf149f2ca
	v_mov_b32_e32 v130, 0xf149f2ca
	v_mov_b32_e32 v131, 0xf149f2ca
	s_branch .LBB0_430
.Latt_u1_4:
	ds_read_b128 v[116:119], v194 offset:32768
	ds_read_b128 v[120:123], v193 offset:32768
	ds_read_b128 v[124:127], v194 offset:36864
	s_waitcnt lgkmcnt(2)
	v_mfma_f32_16x16x32_bf16 v[116:119], v[116:119], v[44:47], v[132:135]
	ds_read_b128 v[206:209], v193 offset:36864
	s_waitcnt lgkmcnt(2)
	v_mfma_f32_16x16x32_bf16 v[128:131], v[120:123], v[52:55], v[116:119]
	s_nop 4
	ds_read_b128 v[116:119], v194 offset:40960
	s_waitcnt lgkmcnt(2)
	v_mfma_f32_16x16x32_bf16 v[120:123], v[124:127], v[44:47], v[132:135]
	ds_read_b128 v[210:213], v193 offset:40960
	s_waitcnt lgkmcnt(2)
	v_mfma_f32_16x16x32_bf16 v[124:127], v[206:209], v[52:55], v[120:123]
	ds_read_b128 v[206:209], v194 offset:45056
	s_waitcnt lgkmcnt(2)
	v_mfma_f32_16x16x32_bf16 v[116:119], v[116:119], v[44:47], v[132:135]
	ds_read_b128 v[214:217], v193 offset:45056
	s_waitcnt lgkmcnt(2)
	v_mfma_f32_16x16x32_bf16 v[120:123], v[210:213], v[52:55], v[116:119]
	s_waitcnt lgkmcnt(1)
	v_mfma_f32_16x16x32_bf16 v[116:119], v[206:209], v[44:47], v[132:135]
	s_waitcnt lgkmcnt(0)
	v_mfma_f32_16x16x32_bf16 v[116:119], v[214:217], v[52:55], v[116:119]
